# v48: S5 scan loop prefetches the next iteration's 32 loads into a shadow register set
# baseline (speedup 1.0000x reference)
.LBB0_1202:
	s_waitcnt vmcnt(0)
	s_barrier
	s_waitcnt vmcnt(0)
	v_mov_b32_e32 v0, v173
	s_movk_i32 s2, 0x80
	s_lshl_b32 s20, s10, 10
	s_waitcnt vmcnt(0) lgkmcnt(0)
	s_barrier
	s_nop 0
	v_cmp_gt_i32_e32 vcc, s2, v0
	s_and_saveexec_b64 s[12:13], vcc
	s_cbranch_execz .LBB0_1205
	v_readlane_b32 s2, v255, 7
	v_readlane_b32 s3, v255, 8
	s_add_i32 s2, s10, s2
	s_ashr_i32 s3, s2, 31
	s_lshl_b64 s[2:3], s[2:3], 9
	s_add_u32 s2, s64, s2
	v_and_b32_e32 v4, 63, v0
	s_addc_u32 s3, s65, s3
	v_lshlrev_b32_e32 v2, 3, v4
	v_mov_b32_e32 v3, v1
	v_lshl_add_u64 v[2:3], s[2:3], 0, v[2:3]
	v_add_co_u32_e32 v2, vcc, 0xd604000, v2
	v_lshrrev_b32_e32 v0, 6, v0
	s_nop 0
	v_addc_co_u32_e32 v3, vcc, 0, v3, vcc
	global_load_dwordx2 v[2:3], v[2:3], off
	v_add_u32_e32 v6, s38, v0
	v_lshl_add_u32 v6, v6, 7, s20
	v_ashrrev_i32_e32 v7, 31, v6
	v_mov_b32_e32 v14, 0
	v_lshlrev_b64 v[6:7], 9, v[6:7]
	v_mov_b32_e32 v5, v1
	s_mov_b32 s14, -16
	v_lshlrev_b32_e32 v0, 1, v4
	v_lshlrev_b32_e32 v4, 2, v4
	v_lshl_add_u64 v[6:7], s[64:65], 0, v[6:7]
	v_mov_b32_e32 v15, v14
	s_waitcnt vmcnt(0)
	v_pk_mov_b32 v[8:9], v[2:3], v[2:3] op_sel:[1,0]
	v_lshl_add_u64 v[82:83], v[6:7], 0, v[4:5]
	v_add_co_u32_e32 v86, vcc, 0x10701000, v82
	s_nop 1
	v_addc_co_u32_e32 v87, vcc, 0, v83, vcc
	v_add_co_u32_e32 v84, vcc, 0x10700000, v82
	s_nop 1
	v_addc_co_u32_e32 v85, vcc, 0, v83, vcc
	global_load_dword v50, v[86:87], off
	global_load_dword v51, v[86:87], off offset:256
	global_load_dword v52, v[86:87], off offset:512
	global_load_dword v53, v[86:87], off offset:768
	global_load_dword v54, v[86:87], off offset:1024
	global_load_dword v55, v[86:87], off offset:1280
	global_load_dword v56, v[86:87], off offset:1536
	global_load_dword v57, v[86:87], off offset:1792
	global_load_dword v58, v[86:87], off offset:2048
	global_load_dword v59, v[86:87], off offset:2304
	global_load_dword v60, v[86:87], off offset:2560
	global_load_dword v61, v[86:87], off offset:2816
	global_load_dword v62, v[86:87], off offset:3072
	global_load_dword v63, v[86:87], off offset:3328
	global_load_dword v64, v[86:87], off offset:3584
	global_load_dword v65, v[86:87], off offset:3840
	global_load_dword v66, v[84:85], off
	global_load_dword v67, v[84:85], off offset:256
	global_load_dword v68, v[84:85], off offset:512
	global_load_dword v69, v[84:85], off offset:768
	global_load_dword v70, v[84:85], off offset:1024
	global_load_dword v71, v[84:85], off offset:1280
	global_load_dword v72, v[84:85], off offset:1536
	global_load_dword v73, v[84:85], off offset:1792
	global_load_dword v74, v[84:85], off offset:2048
	global_load_dword v75, v[84:85], off offset:2304
	global_load_dword v76, v[84:85], off offset:2560
	global_load_dword v77, v[84:85], off offset:2816
	global_load_dword v78, v[84:85], off offset:3072
	global_load_dword v79, v[84:85], off offset:3328
	global_load_dword v80, v[84:85], off offset:3584
	global_load_dword v81, v[84:85], off offset:3840
	s_waitcnt vmcnt(0)
	s_branch .Lscan_body
.LBB0_1204:
	s_waitcnt vmcnt(62)
.Lscan_body:
	s_mov_b64 s[2:3], 0x2000
	v_lshl_add_u64 v[10:11], v[6:7], 0, v[4:5]
	v_lshl_add_u64 v[12:13], v[6:7], 0, v[0:1]
	v_lshl_add_u64 v[6:7], v[6:7], 0, s[2:3]
	s_mov_b32 s2, 0x10701000
	v_add_co_u32_e64 v20, s[2:3], s2, v10
	v_cvt_pk_bf16_f32 v26, v14, s0
	s_nop 0
	v_addc_co_u32_e64 v21, s[2:3], 0, v11, s[2:3]
	v_add_co_u32_e64 v22, s[2:3], s75, v12
	v_cvt_pk_bf16_f32 v27, v15, s0
	s_nop 0
	v_addc_co_u32_e64 v23, s[2:3], 0, v13, s[2:3]
	s_mov_b32 s2, 0xd701000
	s_nop 0
	v_add_co_u32_e64 v12, s[2:3], s2, v12
	v_pk_mul_f32 v[16:17], v[2:3], v[14:15]
	v_pk_mul_f32 v[14:15], v[8:9], v[14:15]
	v_add_co_u32_e32 v18, vcc, 0x10700000, v10
	v_addc_co_u32_e64 v13, s[2:3], 0, v13, s[2:3]
	v_sub_f32_e32 v32, v16, v17
	v_add_f32_e32 v33, v14, v15
	v_addc_co_u32_e32 v19, vcc, 0, v11, vcc
	v_mov_b32_e32 v36, v50
	v_mov_b32_e32 v37, v51
	v_mov_b32_e32 v10, v52
	v_mov_b32_e32 v11, v53
	v_mov_b32_e32 v38, v54
	v_mov_b32_e32 v39, v55
	v_mov_b32_e32 v14, v56
	v_mov_b32_e32 v15, v57
	v_mov_b32_e32 v40, v58
	v_mov_b32_e32 v41, v59
	v_mov_b32_e32 v16, v60
	v_mov_b32_e32 v17, v61
	v_mov_b32_e32 v42, v62
	v_mov_b32_e32 v43, v63
	v_mov_b32_e32 v24, v64
	v_mov_b32_e32 v25, v65
	s_nop 0
	global_store_short v[12:13], v26, off offset:-4096
	global_store_short v[22:23], v27, off offset:128
	v_mov_b32_e32 v34, v66
	v_mov_b32_e32 v35, v67
	v_mov_b32_e32 v20, v68
	v_mov_b32_e32 v21, v69
	v_mov_b32_e32 v44, v70
	v_mov_b32_e32 v45, v71
	v_mov_b32_e32 v26, v72
	v_mov_b32_e32 v27, v73
	v_mov_b32_e32 v46, v74
	v_mov_b32_e32 v47, v75
	v_mov_b32_e32 v28, v76
	v_mov_b32_e32 v29, v77
	v_mov_b32_e32 v48, v78
	v_mov_b32_e32 v49, v79
	v_mov_b32_e32 v30, v80
	v_mov_b32_e32 v31, v81
	s_cmp_lt_i32 s14, 0x60
	s_cbranch_scc0 .Lscan_nopf
	v_lshl_add_u64 v[82:83], v[6:7], 0, v[4:5]
	v_add_co_u32_e32 v86, vcc, 0x10701000, v82
	s_nop 1
	v_addc_co_u32_e32 v87, vcc, 0, v83, vcc
	v_add_co_u32_e32 v84, vcc, 0x10700000, v82
	s_nop 1
	v_addc_co_u32_e32 v85, vcc, 0, v83, vcc
	global_load_dword v50, v[86:87], off
	global_load_dword v51, v[86:87], off offset:256
	global_load_dword v52, v[86:87], off offset:512
	global_load_dword v53, v[86:87], off offset:768
	global_load_dword v54, v[86:87], off offset:1024
	global_load_dword v55, v[86:87], off offset:1280
	global_load_dword v56, v[86:87], off offset:1536
	global_load_dword v57, v[86:87], off offset:1792
	global_load_dword v58, v[86:87], off offset:2048
	global_load_dword v59, v[86:87], off offset:2304
	global_load_dword v60, v[86:87], off offset:2560
	global_load_dword v61, v[86:87], off offset:2816
	global_load_dword v62, v[86:87], off offset:3072
	global_load_dword v63, v[86:87], off offset:3328
	global_load_dword v64, v[86:87], off offset:3584
	global_load_dword v65, v[86:87], off offset:3840
	global_load_dword v66, v[84:85], off
	global_load_dword v67, v[84:85], off offset:256
	global_load_dword v68, v[84:85], off offset:512
	global_load_dword v69, v[84:85], off offset:768
	global_load_dword v70, v[84:85], off offset:1024
	global_load_dword v71, v[84:85], off offset:1280
	global_load_dword v72, v[84:85], off offset:1536
	global_load_dword v73, v[84:85], off offset:1792
	global_load_dword v74, v[84:85], off offset:2048
	global_load_dword v75, v[84:85], off offset:2304
	global_load_dword v76, v[84:85], off offset:2560
	global_load_dword v77, v[84:85], off offset:2816
	global_load_dword v78, v[84:85], off offset:3072
	global_load_dword v79, v[84:85], off offset:3328
	global_load_dword v80, v[84:85], off offset:3584
	global_load_dword v81, v[84:85], off offset:3840
.Lscan_nopf:
	global_store_short v[22:23], v1, off offset:256
	global_store_short v[22:23], v1, off offset:384
	global_store_short v[22:23], v1, off offset:768
	global_store_short v[22:23], v1, off offset:896
	global_store_short v[22:23], v1, off offset:1280
	global_store_short v[22:23], v1, off offset:1408
	global_store_short v[22:23], v1, off offset:1792
	global_store_short v[22:23], v1, off offset:1920
	global_store_short v[22:23], v1, off offset:2304
	global_store_short v[22:23], v1, off offset:2432
	global_store_short v[22:23], v1, off offset:2816
	global_store_short v[22:23], v1, off offset:2944
	global_store_short v[22:23], v1, off offset:3328
	global_store_short v[22:23], v1, off offset:3456
	global_store_short v[22:23], v1, off offset:3840
	global_store_short v[22:23], v1, off offset:3968
	global_store_short v[12:13], v1, off offset:256
	global_store_short v[12:13], v1, off offset:384
	global_store_short v[12:13], v1, off offset:768
	global_store_short v[12:13], v1, off offset:896
	global_store_short v[12:13], v1, off offset:1280
	global_store_short v[12:13], v1, off offset:1408
	global_store_short v[12:13], v1, off offset:1792
	global_store_short v[12:13], v1, off offset:1920
	global_store_short v[12:13], v1, off offset:2304
	global_store_short v[12:13], v1, off offset:2432
	global_store_short v[12:13], v1, off offset:2816
	global_store_short v[12:13], v1, off offset:2944
	global_store_short v[12:13], v1, off offset:3328
	global_store_short v[12:13], v1, off offset:3456
	global_store_short v[12:13], v1, off offset:3840
	global_store_short v[12:13], v1, off offset:3968
	s_add_i32 s14, s14, 16
	s_cmpk_lt_u32 s14, 0x70
	v_add_f32_e32 v18, v34, v32
	v_add_f32_e32 v32, v33, v35
	v_cvt_pk_bf16_f32 v19, v18, s0
	v_cvt_pk_bf16_f32 v34, v32, s0
	v_pk_mul_f32 v[32:33], v[8:9], v[32:33] op_sel_hi:[1,0]
	global_store_short v[22:23], v19, off offset:512
	global_store_short v[22:23], v34, off offset:640
	v_pk_fma_f32 v[34:35], v[2:3], v[18:19], v[32:33] neg_lo:[0,0,1] neg_hi:[0,0,1]
	v_pk_fma_f32 v[18:19], v[2:3], v[18:19], v[32:33] op_sel_hi:[1,0,1]
	s_nop 0
	v_mov_b32_e32 v35, v19
	v_pk_add_f32 v[18:19], v[20:21], v[34:35]
	s_nop 0
	v_cvt_pk_bf16_f32 v32, v18, s0
	v_cvt_pk_bf16_f32 v33, v19, s0
	v_pk_mul_f32 v[20:21], v[2:3], v[18:19]
	v_pk_mul_f32 v[18:19], v[2:3], v[18:19] op_sel:[0,1] op_sel_hi:[1,0]
	v_sub_f32_e32 v20, v20, v21
	v_add_f32_e32 v19, v18, v19
	v_add_f32_e32 v18, v44, v20
	v_add_f32_e32 v20, v45, v19
	global_store_short v[22:23], v32, off offset:1024
	global_store_short v[22:23], v33, off offset:1152
	v_cvt_pk_bf16_f32 v19, v18, s0
	v_cvt_pk_bf16_f32 v32, v20, s0
	v_pk_mul_f32 v[20:21], v[8:9], v[20:21] op_sel_hi:[1,0]
	global_store_short v[22:23], v19, off offset:1536
	global_store_short v[22:23], v32, off offset:1664
	v_pk_fma_f32 v[32:33], v[2:3], v[18:19], v[20:21] neg_lo:[0,0,1] neg_hi:[0,0,1]
	v_pk_fma_f32 v[18:19], v[2:3], v[18:19], v[20:21] op_sel_hi:[1,0,1]
	s_nop 0
	v_mov_b32_e32 v33, v19
	v_pk_add_f32 v[18:19], v[26:27], v[32:33]
	s_nop 0
	v_cvt_pk_bf16_f32 v26, v18, s0
	v_cvt_pk_bf16_f32 v27, v19, s0
	v_pk_mul_f32 v[20:21], v[2:3], v[18:19]
	v_pk_mul_f32 v[18:19], v[2:3], v[18:19] op_sel:[0,1] op_sel_hi:[1,0]
	v_sub_f32_e32 v20, v20, v21
	v_add_f32_e32 v19, v18, v19
	v_add_f32_e32 v18, v46, v20
	v_add_f32_e32 v20, v47, v19
	global_store_short v[22:23], v26, off offset:2048
	global_store_short v[22:23], v27, off offset:2176
	v_cvt_pk_bf16_f32 v19, v18, s0
	v_cvt_pk_bf16_f32 v26, v20, s0
	v_pk_mul_f32 v[20:21], v[8:9], v[20:21] op_sel_hi:[1,0]
	global_store_short v[22:23], v19, off offset:2560
	global_store_short v[22:23], v26, off offset:2688
	v_pk_fma_f32 v[26:27], v[2:3], v[18:19], v[20:21] neg_lo:[0,0,1] neg_hi:[0,0,1]
	v_pk_fma_f32 v[18:19], v[2:3], v[18:19], v[20:21] op_sel_hi:[1,0,1]
	s_nop 0
	v_mov_b32_e32 v27, v19
	v_pk_add_f32 v[18:19], v[28:29], v[26:27]
	s_nop 0
	v_cvt_pk_bf16_f32 v26, v18, s0
	v_cvt_pk_bf16_f32 v27, v19, s0
	v_pk_mul_f32 v[20:21], v[2:3], v[18:19]
	v_pk_mul_f32 v[18:19], v[2:3], v[18:19] op_sel:[0,1] op_sel_hi:[1,0]
	v_sub_f32_e32 v20, v20, v21
	v_add_f32_e32 v19, v18, v19
	v_add_f32_e32 v18, v48, v20
	v_add_f32_e32 v20, v49, v19
	global_store_short v[22:23], v26, off offset:3072
	global_store_short v[22:23], v27, off offset:3200
	v_cvt_pk_bf16_f32 v19, v18, s0
	v_cvt_pk_bf16_f32 v26, v20, s0
	v_pk_mul_f32 v[20:21], v[8:9], v[20:21] op_sel_hi:[1,0]
	global_store_short v[22:23], v19, off offset:3584
	global_store_short v[22:23], v26, off offset:3712
	v_pk_fma_f32 v[22:23], v[2:3], v[18:19], v[20:21] neg_lo:[0,0,1] neg_hi:[0,0,1]
	v_pk_fma_f32 v[18:19], v[2:3], v[18:19], v[20:21] op_sel_hi:[1,0,1]
	s_nop 0
	v_mov_b32_e32 v23, v19
	v_pk_add_f32 v[18:19], v[30:31], v[22:23]
	s_nop 0
	v_cvt_pk_bf16_f32 v22, v18, s0
	v_cvt_pk_bf16_f32 v23, v19, s0
	v_pk_mul_f32 v[20:21], v[2:3], v[18:19]
	v_pk_mul_f32 v[18:19], v[2:3], v[18:19] op_sel:[0,1] op_sel_hi:[1,0]
	v_sub_f32_e32 v20, v20, v21
	v_add_f32_e32 v19, v18, v19
	v_add_f32_e32 v18, v36, v20
	v_add_f32_e32 v20, v37, v19
	global_store_short v[12:13], v22, off
	global_store_short v[12:13], v23, off offset:128
	v_cvt_pk_bf16_f32 v19, v18, s0
	v_cvt_pk_bf16_f32 v22, v20, s0
	v_pk_mul_f32 v[20:21], v[8:9], v[20:21] op_sel_hi:[1,0]
	global_store_short v[12:13], v19, off offset:512
	global_store_short v[12:13], v22, off offset:640
	v_pk_fma_f32 v[22:23], v[2:3], v[18:19], v[20:21] neg_lo:[0,0,1] neg_hi:[0,0,1]
	v_pk_fma_f32 v[18:19], v[2:3], v[18:19], v[20:21] op_sel_hi:[1,0,1]
	s_nop 0
	v_mov_b32_e32 v23, v19
	v_pk_add_f32 v[10:11], v[10:11], v[22:23]
	s_nop 0
	v_cvt_pk_bf16_f32 v20, v10, s0
	v_cvt_pk_bf16_f32 v21, v11, s0
	v_pk_mul_f32 v[18:19], v[2:3], v[10:11]
	v_pk_mul_f32 v[10:11], v[2:3], v[10:11] op_sel:[0,1] op_sel_hi:[1,0]
	v_sub_f32_e32 v18, v18, v19
	v_add_f32_e32 v11, v10, v11
	v_add_f32_e32 v10, v38, v18
	v_add_f32_e32 v18, v39, v11
	global_store_short v[12:13], v20, off offset:1024
	global_store_short v[12:13], v21, off offset:1152
	v_cvt_pk_bf16_f32 v11, v10, s0
	v_cvt_pk_bf16_f32 v20, v18, s0
	v_pk_mul_f32 v[18:19], v[8:9], v[18:19] op_sel_hi:[1,0]
	global_store_short v[12:13], v11, off offset:1536
	global_store_short v[12:13], v20, off offset:1664
	v_pk_fma_f32 v[20:21], v[2:3], v[10:11], v[18:19] neg_lo:[0,0,1] neg_hi:[0,0,1]
	v_pk_fma_f32 v[10:11], v[2:3], v[10:11], v[18:19] op_sel_hi:[1,0,1]
	s_nop 0
	v_mov_b32_e32 v21, v11
	v_pk_add_f32 v[10:11], v[14:15], v[20:21]
	s_nop 0
	v_cvt_pk_bf16_f32 v18, v10, s0
	v_cvt_pk_bf16_f32 v19, v11, s0
	v_pk_mul_f32 v[14:15], v[2:3], v[10:11]
	v_pk_mul_f32 v[10:11], v[2:3], v[10:11] op_sel:[0,1] op_sel_hi:[1,0]
	v_sub_f32_e32 v14, v14, v15
	v_add_f32_e32 v11, v10, v11
	v_add_f32_e32 v10, v40, v14
	v_add_f32_e32 v14, v41, v11
	global_store_short v[12:13], v18, off offset:2048
	global_store_short v[12:13], v19, off offset:2176
	v_cvt_pk_bf16_f32 v11, v10, s0
	v_cvt_pk_bf16_f32 v18, v14, s0
	v_pk_mul_f32 v[14:15], v[8:9], v[14:15] op_sel_hi:[1,0]
	global_store_short v[12:13], v11, off offset:2560
	global_store_short v[12:13], v18, off offset:2688
	v_pk_fma_f32 v[18:19], v[2:3], v[10:11], v[14:15] neg_lo:[0,0,1] neg_hi:[0,0,1]
	v_pk_fma_f32 v[10:11], v[2:3], v[10:11], v[14:15] op_sel_hi:[1,0,1]
	s_nop 0
	v_mov_b32_e32 v19, v11
	v_pk_add_f32 v[10:11], v[16:17], v[18:19]
	s_nop 0
	v_cvt_pk_bf16_f32 v16, v10, s0
	v_cvt_pk_bf16_f32 v17, v11, s0
	v_pk_mul_f32 v[14:15], v[2:3], v[10:11]
	v_pk_mul_f32 v[10:11], v[2:3], v[10:11] op_sel:[0,1] op_sel_hi:[1,0]
	v_sub_f32_e32 v14, v14, v15
	v_add_f32_e32 v11, v10, v11
	v_add_f32_e32 v10, v42, v14
	v_add_f32_e32 v14, v43, v11
	global_store_short v[12:13], v16, off offset:3072
	global_store_short v[12:13], v17, off offset:3200
	v_cvt_pk_bf16_f32 v11, v10, s0
	v_cvt_pk_bf16_f32 v16, v14, s0
	v_pk_mul_f32 v[14:15], v[8:9], v[14:15] op_sel_hi:[1,0]
	global_store_short v[12:13], v11, off offset:3584
	global_store_short v[12:13], v16, off offset:3712
	v_pk_fma_f32 v[12:13], v[2:3], v[10:11], v[14:15] neg_lo:[0,0,1] neg_hi:[0,0,1]
	v_pk_fma_f32 v[10:11], v[2:3], v[10:11], v[14:15] op_sel_hi:[1,0,1]
	s_nop 0
	v_mov_b32_e32 v13, v11
	v_pk_add_f32 v[14:15], v[24:25], v[12:13]
	s_cbranch_scc1 .LBB0_1204
